# peer_out streaming H-row / top-value loads with nt hint (do not pollute L2/MALL holding the fp6 tables)
# speedup vs baseline: 1.0145x; 1.0145x over previous
; DI int otid() { int t = __builtin_amdgcn_workitem_id_x(); asm volatile("" : "+v"(t)); return t; }
; DI float bflo(unsigned w) { return __uint_as_float(w << 16); }
; DI float bfhi(unsigned w) { return __uint_as_float(w & 0xffff0000u); }
; DI void phase_peer_out(const Params& p, char* lds) {
;     ...
;   const int tid = otid(), lane = tid & 63, wave = tid >> 6, hb = lane >> 5, l5 = lane & 31;
;   int* sidx = (int*)lds + wave * 384; float* sw = (float*)(sidx + 128);
;   const u16* H = (const u16*)(ws + OFF_H); const unsigned* TV = (const unsigned*)(ws + OFF_TOPV);
;   const unsigned char* U6 = (const unsigned char*)(ws + OFF_U8) + 24 * l5; const unsigned char* V6 = (const unsigned char*)(ws + OFF_V8) + 24 * l5;
;   const float* USC = (const float*)(ws + OFF_USC); const float* VSC = (const float*)(ws + OFF_VSC);
;   const float* g3 = p.in[23]; const float* b3 = p.in[24];
;   int ci = 0, cj = 0; const bool cval = lane < 50;
;   if (cval) { int rem = lane, i = 0; while (true) { const int cnt = 16 / (i + 1); if (rem < cnt) break; rem -= cnt; ++i; } ci = i; cj = rem; }
;   const int flat = ci * 16 + cj;
;   for (int t = blockIdx.x * 8 + wave; t < T_TOK; t += gridDim.x * 8) {
;     f32x2 x2[16];
; #pragma unroll
;     for (int i = 0; i < 4; ++i) {
;       const uint4 hv = *(const uint4*)(H + (size_t)t * 1024 + 32 * l5 + 8 * i);
;       x2[4 * i] = f32x2{bflo(hv.x), bfhi(hv.x)}; x2[4 * i + 1] = f32x2{bflo(hv.y), bfhi(hv.y)}; x2[4 * i + 2] = f32x2{bflo(hv.z), bfhi(hv.z)}; x2[4 * i + 3] = f32x2{bflo(hv.w), bfhi(hv.w)};
;     }
;     float hval[8]; int hidx[8];
; #pragma unroll
;     for (int hq = 0; hq < 8; ++hq) {
;       const unsigned ka = TV[(size_t)t * 256 + (2 * hq) * 16 + ci], kb = TV[(size_t)t * 256 + (2 * hq + 1) * 16 + cj];
;       const float va = __uint_as_float(ka & 0xFFFFFF80u), vb = __uint_as_float(kb & 0xFFFFFF80u);
;       const int ia = 127 - (int)(ka & 127u), ib = 127 - (int)(kb & 127u);
;       hval[hq] = cval ? va + vb : -INFINITY; hidx[hq] = ia * 128 + ib;
;     }
.LBB0_1184:
	s_or_b64 exec, exec, s[2:3]
	v_ashrrev_i32_e32 v1, 6, v222
	v_readlane_b32 s0, v250, 27
	s_nop 1
	v_add_u32_e32 v60, s0, v1
	s_mov_b32 s0, 0x10000
	v_cmp_gt_i32_e64 s[0:1], s0, v60
	s_and_saveexec_b64 s[2:3], s[0:1]
	s_cbranch_execz .LBB0_1211
	s_movk_i32 s0, 0x600
	v_and_b32_e32 v5, 31, v222
	v_mul_lo_u32 v1, v1, s0
	v_readlane_b32 s0, v250, 52
	v_mul_u32_u24_e32 v2, 24, v5
	v_mov_b32_e32 v3, 0
	v_readlane_b32 s1, v250, 53
	v_add_u32_e32 v110, 0, v1
	v_lshl_add_u32 v1, v58, 4, v56
	v_lshl_add_u64 v[62:63], s[0:1], 0, v[2:3]
	v_readlane_b32 s0, v250, 54
	v_readlane_b32 s1, v250, 55
	v_sub_u32_e32 v111, 0xff, v1
	v_and_b32_e32 v1, 64, v223
	v_lshl_add_u64 v[64:65], s[0:1], 0, v[2:3]
	v_lshlrev_b32_e32 v2, 6, v5
	v_lshrrev_b32_e32 v4, 5, v0
	v_lshl_add_u64 v[66:67], s[24:25], 0, v[2:3]
	v_add_u32_e32 v7, 64, v1
	v_cmp_gt_u32_e64 s[0:1], 32, v0
	v_lshl_add_u32 v112, v0, 2, v110
	v_xor_b32_e32 v0, 32, v223
	v_readlane_b32 s16, v250, 30
	v_cmp_lt_i32_e64 s[2:3], v0, v7
	v_readlane_b32 s17, v250, 31
	v_readlane_b32 s18, v250, 32
	v_readlane_b32 s19, v250, 33
	v_cndmask_b32_e64 v0, v223, v0, s[2:3]
	v_lshlrev_b32_e32 v2, 7, v5
	v_readlane_b32 s30, v250, 44
	v_readlane_b32 s31, v250, 45
	v_readlane_b32 s16, v250, 56
	v_lshl_add_u32 v6, v5, 2, v110
	v_lshlrev_b32_e32 v8, 8, v4
	v_lshlrev_b32_e32 v113, 2, v0
	v_lshl_add_u64 v[0:1], s[30:31], 0, v[2:3]
	v_lshlrev_b32_e32 v4, 6, v4
	v_mov_b32_e32 v5, v3
	v_readlane_b32 s17, v250, 57
	v_lshl_add_u64 v[68:69], v[0:1], 0, v[4:5]
	v_readlane_b32 s18, v250, 58
	v_lshl_add_u64 v[0:1], s[16:17], 0, v[2:3]
	v_lshl_add_u64 v[70:71], v[0:1], 0, v[4:5]
	v_xor_b32_e32 v0, 8, v223
	v_cmp_lt_i32_e64 s[2:3], v0, v7
	v_readlane_b32 s19, v250, 59
	v_readlane_b32 s20, v250, 34
	v_cndmask_b32_e64 v0, v223, v0, s[2:3]
	v_lshlrev_b32_e32 v114, 2, v0
	v_xor_b32_e32 v0, 4, v223
	v_cmp_lt_i32_e64 s[2:3], v0, v7
	v_readlane_b32 s21, v250, 35
	v_readlane_b32 s22, v250, 36
	v_cndmask_b32_e64 v0, v223, v0, s[2:3]
	v_lshlrev_b32_e32 v115, 2, v0
	v_xor_b32_e32 v0, 2, v223
	v_cmp_lt_i32_e64 s[2:3], v0, v7
	v_readlane_b32 s23, v250, 37
	v_readlane_b32 s24, v250, 38
	v_cndmask_b32_e64 v0, v223, v0, s[2:3]
	v_lshlrev_b32_e32 v116, 2, v0
	v_xor_b32_e32 v0, 1, v223
	v_cmp_lt_i32_e64 s[2:3], v0, v7
	v_readlane_b32 s25, v250, 39
	v_readlane_b32 s26, v250, 40
	v_cndmask_b32_e64 v0, v223, v0, s[2:3]
	v_lshlrev_b32_e32 v117, 2, v0
	v_and_b32_e32 v0, 16, v222
	v_cmp_eq_u32_e64 s[2:3], 0, v0
	v_xor_b32_e32 v0, 16, v223
	v_cmp_lt_i32_e64 s[4:5], v0, v7
	v_readlane_b32 s27, v250, 41
	v_readlane_b32 s28, v250, 42
	v_cndmask_b32_e64 v0, v223, v0, s[4:5]
	v_lshlrev_b32_e32 v118, 2, v0
	v_and_b32_e32 v0, 8, v222
	v_cmp_eq_u32_e64 s[4:5], 0, v0
	v_and_b32_e32 v0, 4, v222
	v_cmp_eq_u32_e64 s[6:7], 0, v0
	v_and_b32_e32 v0, 2, v222
	v_cmp_eq_u32_e64 s[8:9], 0, v0
	v_and_b32_e32 v0, 1, v222
	v_readlane_b32 s29, v250, 43
	v_cmp_eq_u32_e64 s[10:11], 0, v0
	v_lshl_add_u64 v[0:1], s[18:19], 0, v[2:3]
	v_mov_b32_e32 v59, v3
	v_ashrrev_i32_e32 v57, 31, v56
	v_lshl_add_u64 v[72:73], v[0:1], 0, v[4:5]
	s_mov_b64 s[18:19], 0
	v_mov_b32_e32 v119, 0xff800000
	v_bfrev_b32_e32 v120, 1
	s_movk_i32 s21, 0xff00
	s_movk_i32 s22, 0x3fff
	s_movk_i32 s23, 0x300
	v_add_u32_e32 v121, v6, v8
	s_mov_b32 s24, 0x378e98ab
	s_mov_b32 s25, 0x3b7cd369
	s_mov_b32 s26, 0xbcc618b2
	s_mov_b32 s27, 0x3dda74e4
	s_mov_b32 s28, 0x3f228afd
	s_mov_b32 s29, 0x3e03c728
	s_mov_b32 s30, 0xbfb8aa3b
	s_mov_b32 s31, 0x42ce8ed0
	s_mov_b32 s33, 0xc2b17218
	v_mov_b32_e32 v122, 0x3ba10414
	s_brev_b32 s34, -2
	s_mov_b32 s20, 0x3f9837f0
	v_mov_b32_e32 v123, 0x3727c5ac
	s_mov_b32 s35, 0x800000
	s_mov_b32 s36, 0xffff
	v_mov_b32_e32 v124, 0xb9c68948
	v_mov_b32_e32 v125, 0x7f800000
	v_ashrrev_i32_e32 v61, 31, v60
	v_mov_b32_e32 v248, v60
	v_mov_b32_e32 v249, v61
	v_lshlrev_b64 v[36:37], 10, v[248:249]
	v_lshl_add_u64 v[36:37], s[14:15], 0, v[36:37]
	v_lshl_add_u64 v[34:35], v[56:57], 2, v[36:37]
	v_lshl_add_u64 v[32:33], v[58:59], 2, v[36:37]
	global_load_dword v231, v[34:35], off offset:64 nt
	global_load_dword v230, v[32:33], off nt
	v_lshlrev_b64 v[248:249], 11, v[248:249]
	v_lshl_add_u64 v[36:37], v[66:67], 0, v[248:249]
	global_load_dwordx4 v[232:235], v[36:37], off offset:48 nt
	global_load_dwordx4 v[236:239], v[36:37], off offset:32 nt
	global_load_dwordx4 v[240:243], v[36:37], off offset:16 nt
	global_load_dwordx4 v[244:247], v[36:37], off nt
	global_load_dword v228, v[32:33], off offset:128 nt
	global_load_dword v226, v[32:33], off offset:256 nt
	global_load_dword v224, v[32:33], off offset:384 nt
	global_load_dword v222, v[32:33], off offset:512 nt
	global_load_dword v220, v[32:33], off offset:640 nt
	global_load_dword v218, v[32:33], off offset:768 nt
	global_load_dword v216, v[32:33], off offset:896 nt
	global_load_dword v229, v[34:35], off offset:192 nt
	global_load_dword v227, v[34:35], off offset:320 nt
	global_load_dword v225, v[34:35], off offset:448 nt
	global_load_dword v223, v[34:35], off offset:576 nt
	global_load_dword v221, v[34:35], off offset:704 nt
	global_load_dword v219, v[34:35], off offset:832 nt
	global_load_dword v217, v[34:35], off offset:960 nt
	s_waitcnt vmcnt(0)
	global_load_dwordx4 v[184:187], v[68:69], off
	global_load_dwordx4 v[188:191], v[68:69], off offset:16
	global_load_dwordx4 v[192:195], v[68:69], off offset:32
	global_load_dwordx4 v[196:199], v[68:69], off offset:48
	global_load_dwordx4 v[200:203], v[70:71], off
	global_load_dwordx4 v[204:207], v[70:71], off offset:16
	global_load_dwordx4 v[208:211], v[70:71], off offset:32
	global_load_dwordx4 v[212:215], v[70:71], off offset:48
	s_waitcnt vmcnt(0)
	s_branch .LBB0_1187

; DI float bflo(unsigned w) { return __uint_as_float(w << 16); }
; DI float bfhi(unsigned w) { return __uint_as_float(w & 0xffff0000u); }
; DI void phase_peer_out(const Params& p, char* lds) {
;     ...
;   for (int t = blockIdx.x * 8 + wave; t < T_TOK; t += gridDim.x * 8) {
;     f32x2 x2[16];
; #pragma unroll
;     for (int i = 0; i < 4; ++i) {
;       const uint4 hv = *(const uint4*)(H + (size_t)t * 1024 + 32 * l5 + 8 * i);
;       x2[4 * i] = f32x2{bflo(hv.x), bfhi(hv.x)}; x2[4 * i + 1] = f32x2{bflo(hv.y), bfhi(hv.y)}; x2[4 * i + 2] = f32x2{bflo(hv.z), bfhi(hv.z)}; x2[4 * i + 3] = f32x2{bflo(hv.w), bfhi(hv.w)};
;     }
;     float hval[8]; int hidx[8];
; #pragma unroll
;     for (int hq = 0; hq < 8; ++hq) {
;       const unsigned ka = TV[(size_t)t * 256 + (2 * hq) * 16 + ci], kb = TV[(size_t)t * 256 + (2 * hq + 1) * 16 + cj];
;       const float va = __uint_as_float(ka & 0xFFFFFF80u), vb = __uint_as_float(kb & 0xFFFFFF80u);
;       const int ia = 127 - (int)(ka & 127u), ib = 127 - (int)(kb & 127u);
;       hval[hq] = cval ? va + vb : -INFINITY; hidx[hq] = ia * 128 + ib;
;     }
; #pragma unroll
;     for (int hq = 0; hq < 8; ++hq) {
;       const float val = hval[hq];
;       const unsigned vb32 = __float_as_uint(val);
;       const unsigned ukey = cval ? (((vb32 ^ ((vb32 >> 31) ? 0xFFFFFFFFu : 0x80000000u)) & 0xFFFFFF00u) | (unsigned)(255 - flat)) : 0u;
;       int rank = 0;
;       rank_steps10<0>(ukey, flat, rank); rank_steps10<10>(ukey, flat, rank); rank_steps10<20>(ukey, flat, rank); rank_steps10<30>(ukey, flat, rank); rank_steps10<40>(ukey, flat, rank);
.LBB0_1187:
	v_ashrrev_i32_e32 v61, 31, v60
	s_waitcnt vmcnt(4)
	v_mov_b64_e32 v[0:1], v[232:233]
	v_mov_b64_e32 v[2:3], v[234:235]
	v_mov_b64_e32 v[4:5], v[236:237]
	v_mov_b64_e32 v[6:7], v[238:239]
	v_mov_b64_e32 v[8:9], v[240:241]
	v_mov_b64_e32 v[10:11], v[242:243]
	v_mov_b64_e32 v[12:13], v[244:245]
	v_mov_b64_e32 v[14:15], v[246:247]
	v_mov_b64_e32 v[16:17], v[216:217]
	v_mov_b64_e32 v[18:19], v[218:219]
	v_mov_b64_e32 v[20:21], v[220:221]
	v_mov_b64_e32 v[22:23], v[222:223]
	v_mov_b64_e32 v[24:25], v[224:225]
	v_mov_b64_e32 v[26:27], v[226:227]
	v_mov_b64_e32 v[28:29], v[228:229]
	v_mov_b64_e32 v[30:31], v[230:231]
	v_add_u32_e32 v248, s53, v60
	v_ashrrev_i32_e32 v249, 31, v248
	v_lshlrev_b64 v[36:37], 10, v[248:249]
	v_lshl_add_u64 v[36:37], s[14:15], 0, v[36:37]
	v_lshl_add_u64 v[34:35], v[56:57], 2, v[36:37]
	v_lshl_add_u64 v[32:33], v[58:59], 2, v[36:37]
	global_load_dword v231, v[34:35], off offset:64 nt
	global_load_dword v230, v[32:33], off nt
	v_lshlrev_b64 v[248:249], 11, v[248:249]
	v_lshl_add_u64 v[36:37], v[66:67], 0, v[248:249]
	global_load_dwordx4 v[232:235], v[36:37], off offset:48 nt
	global_load_dwordx4 v[236:239], v[36:37], off offset:32 nt
	global_load_dwordx4 v[240:243], v[36:37], off offset:16 nt
	global_load_dwordx4 v[244:247], v[36:37], off nt
	global_load_dword v228, v[32:33], off offset:128 nt
	global_load_dword v226, v[32:33], off offset:256 nt
	global_load_dword v224, v[32:33], off offset:384 nt
	global_load_dword v222, v[32:33], off offset:512 nt
	global_load_dword v220, v[32:33], off offset:640 nt
	global_load_dword v218, v[32:33], off offset:768 nt
	global_load_dword v216, v[32:33], off offset:896 nt
	global_load_dword v229, v[34:35], off offset:192 nt
	global_load_dword v227, v[34:35], off offset:320 nt
	global_load_dword v225, v[34:35], off offset:448 nt
	global_load_dword v223, v[34:35], off offset:576 nt
	global_load_dword v221, v[34:35], off offset:704 nt
	global_load_dword v219, v[34:35], off offset:832 nt
	global_load_dword v217, v[34:35], off offset:960 nt
	v_and_b32_e32 v32, 0xffffff80, v31
	v_and_b32_e32 v33, 0xffffff80, v30
	v_add_f32_e32 v32, v32, v33
	v_cndmask_b32_e32 v33, v119, v32, vcc
	v_cmp_lt_i32_e64 s[12:13], -1, v33
	s_nop 1
	v_cndmask_b32_e64 v34, -1, v120, s[12:13]
	v_xor_b32_e32 v33, v34, v33
	v_and_or_b32 v33, v33, s21, v111
	v_cndmask_b32_e32 v33, 0, v33, vcc
	s_nop 0
	v_readlane_b32 s12, v33, 0
	v_readlane_b32 s17, v33, 2
	v_readlane_b32 s38, v33, 4
	v_cmp_gt_u32_e64 s[12:13], s12, v33
	v_readlane_b32 s40, v33, 6
	v_readlane_b32 s42, v33, 8
	v_cndmask_b32_e64 v34, 0, 1, s[12:13]
	v_cmp_gt_u32_e64 s[12:13], s17, v33
	v_readlane_b32 s44, v33, 10
	v_readlane_b32 s46, v33, 12
	v_cndmask_b32_e64 v35, 0, 1, s[12:13]
	v_cmp_gt_u32_e64 s[12:13], s38, v33
	v_readlane_b32 s48, v33, 14
	v_readlane_b32 s50, v33, 16
	v_cndmask_b32_e64 v36, 0, 1, s[12:13]
	v_cmp_gt_u32_e64 s[12:13], s40, v33
	v_readlane_b32 s52, v33, 18
	v_readlane_b32 s16, v33, 1
	v_cndmask_b32_e64 v37, 0, 1, s[12:13]
	v_cmp_gt_u32_e64 s[12:13], s42, v33
	v_readlane_b32 s37, v33, 3
	v_readlane_b32 s39, v33, 5
	v_cndmask_b32_e64 v38, 0, 1, s[12:13]
	v_cmp_gt_u32_e64 s[12:13], s44, v33
	v_readlane_b32 s41, v33, 7
	v_readlane_b32 s43, v33, 9
	v_cndmask_b32_e64 v39, 0, 1, s[12:13]
	v_cmp_gt_u32_e64 s[12:13], s46, v33
	v_readlane_b32 s45, v33, 11
	v_readlane_b32 s47, v33, 13
	v_cndmask_b32_e64 v40, 0, 1, s[12:13]
	v_cmp_gt_u32_e64 s[12:13], s48, v33
	v_readlane_b32 s49, v33, 15
	v_readlane_b32 s51, v33, 17
	v_cndmask_b32_e64 v41, 0, 1, s[12:13]
	v_cmp_gt_u32_e64 s[12:13], s50, v33
	s_nop 1
	v_cndmask_b32_e64 v42, 0, 1, s[12:13]
	v_cmp_gt_u32_e64 s[12:13], s52, v33
	s_nop 1
	v_cndmask_b32_e64 v43, 0, 1, s[12:13]
	v_cmp_gt_u32_e64 s[12:13], s16, v33
	s_nop 1
	v_addc_co_u32_e64 v34, s[12:13], 0, v34, s[12:13]
	v_cmp_gt_u32_e64 s[12:13], s37, v33
	s_nop 1
	v_addc_co_u32_e64 v34, s[12:13], v34, v35, s[12:13]
	v_cmp_gt_u32_e64 s[12:13], s39, v33
	s_nop 1
	v_addc_co_u32_e64 v34, s[12:13], v34, v36, s[12:13]
	v_cmp_gt_u32_e64 s[12:13], s41, v33
	s_nop 1
	v_addc_co_u32_e64 v34, s[12:13], v34, v37, s[12:13]
	v_cmp_gt_u32_e64 s[12:13], s43, v33
	s_nop 1
	v_addc_co_u32_e64 v34, s[12:13], v34, v38, s[12:13]
	v_cmp_gt_u32_e64 s[12:13], s45, v33
	s_nop 1
	v_addc_co_u32_e64 v34, s[12:13], v34, v39, s[12:13]
	v_cmp_gt_u32_e64 s[12:13], s47, v33
	s_nop 1
	v_addc_co_u32_e64 v34, s[12:13], v34, v40, s[12:13]
	v_cmp_gt_u32_e64 s[12:13], s49, v33
	s_nop 1
	v_addc_co_u32_e64 v34, s[12:13], v34, v41, s[12:13]
; DI void phase_peer_out(const Params& p, char* lds) {
;     ...
; #pragma unroll
;     for (int hq = 0; hq < 8; ++hq) {
;       const float val = hval[hq];
;       const unsigned vb32 = __float_as_uint(val);
;       const unsigned ukey = cval ? (((vb32 ^ ((vb32 >> 31) ? 0xFFFFFFFFu : 0x80000000u)) & 0xFFFFFF00u) | (unsigned)(255 - flat)) : 0u;
;       int rank = 0;
;       rank_steps10<0>(ukey, flat, rank); rank_steps10<10>(ukey, flat, rank); rank_steps10<20>(ukey, flat, rank); rank_steps10<30>(ukey, flat, rank); rank_steps10<40>(ukey, flat, rank);
;       if (cval && rank < 16) { sidx[hq * 16 + rank] = hidx[hq]; sw[hq * 16 + rank] = val; }
	v_cmp_gt_u32_e64 s[12:13], s51, v33
	s_nop 1
	v_addc_co_u32_e64 v34, s[12:13], v34, v42, s[12:13]
	v_readlane_b32 s12, v33, 19
	s_nop 1
	v_cmp_gt_u32_e64 s[12:13], s12, v33
	s_nop 1
	v_addc_co_u32_e64 v34, s[12:13], v34, v43, s[12:13]
	v_readlane_b32 s12, v33, 20
	s_nop 1
	v_cmp_gt_u32_e64 s[12:13], s12, v33
	s_nop 1
	v_cndmask_b32_e64 v35, 0, 1, s[12:13]
	v_readlane_b32 s12, v33, 21
	s_nop 1
	v_cmp_gt_u32_e64 s[12:13], s12, v33
	s_nop 1
	v_addc_co_u32_e64 v34, s[12:13], v34, v35, s[12:13]
	v_readlane_b32 s12, v33, 22
	s_nop 1
	v_cmp_gt_u32_e64 s[12:13], s12, v33
	s_nop 1
	v_cndmask_b32_e64 v35, 0, 1, s[12:13]
	v_readlane_b32 s12, v33, 23
	s_nop 1
	v_cmp_gt_u32_e64 s[12:13], s12, v33
	s_nop 1
	v_addc_co_u32_e64 v34, s[12:13], v34, v35, s[12:13]
	v_readlane_b32 s12, v33, 24
	s_nop 1
	v_cmp_gt_u32_e64 s[12:13], s12, v33
	s_nop 1
	v_cndmask_b32_e64 v35, 0, 1, s[12:13]
	v_readlane_b32 s12, v33, 25
	s_nop 1
	v_cmp_gt_u32_e64 s[12:13], s12, v33
	s_nop 1
	v_addc_co_u32_e64 v34, s[12:13], v34, v35, s[12:13]
	v_readlane_b32 s12, v33, 26
	s_nop 1
	v_cmp_gt_u32_e64 s[12:13], s12, v33
	s_nop 1
	v_cndmask_b32_e64 v35, 0, 1, s[12:13]
	v_readlane_b32 s12, v33, 27
	s_nop 1
	v_cmp_gt_u32_e64 s[12:13], s12, v33
	s_nop 1
	v_addc_co_u32_e64 v34, s[12:13], v34, v35, s[12:13]
	v_readlane_b32 s12, v33, 28
	s_nop 1
	v_cmp_gt_u32_e64 s[12:13], s12, v33
	s_nop 1
	v_cndmask_b32_e64 v35, 0, 1, s[12:13]
	v_readlane_b32 s12, v33, 29
	s_nop 1
	v_cmp_gt_u32_e64 s[12:13], s12, v33
	s_nop 1
	v_addc_co_u32_e64 v34, s[12:13], v34, v35, s[12:13]
	v_readlane_b32 s12, v33, 30
	s_nop 1
	v_cmp_gt_u32_e64 s[12:13], s12, v33
	s_nop 1
	v_cndmask_b32_e64 v35, 0, 1, s[12:13]
	v_readlane_b32 s12, v33, 31
	s_nop 1
	v_cmp_gt_u32_e64 s[12:13], s12, v33
	s_nop 1
	v_addc_co_u32_e64 v34, s[12:13], v34, v35, s[12:13]
	v_readlane_b32 s12, v33, 32
	s_nop 1
	v_cmp_gt_u32_e64 s[12:13], s12, v33
	s_nop 1
	v_cndmask_b32_e64 v35, 0, 1, s[12:13]
	v_readlane_b32 s12, v33, 33
	s_nop 1
	v_cmp_gt_u32_e64 s[12:13], s12, v33
	s_nop 1
	v_addc_co_u32_e64 v34, s[12:13], v34, v35, s[12:13]
	v_readlane_b32 s12, v33, 34
	s_nop 1
	v_cmp_gt_u32_e64 s[12:13], s12, v33
	s_nop 1
	v_cndmask_b32_e64 v35, 0, 1, s[12:13]
	v_readlane_b32 s12, v33, 35
	s_nop 1
	v_cmp_gt_u32_e64 s[12:13], s12, v33
	s_nop 1
	v_addc_co_u32_e64 v34, s[12:13], v34, v35, s[12:13]
	v_readlane_b32 s12, v33, 36
	s_nop 1
	v_cmp_gt_u32_e64 s[12:13], s12, v33
	s_nop 1
	v_cndmask_b32_e64 v35, 0, 1, s[12:13]
	v_readlane_b32 s12, v33, 37
	s_nop 1
	v_cmp_gt_u32_e64 s[12:13], s12, v33
	s_nop 1
	v_addc_co_u32_e64 v34, s[12:13], v34, v35, s[12:13]
	v_readlane_b32 s12, v33, 38
	s_nop 1
	v_cmp_gt_u32_e64 s[12:13], s12, v33
	s_nop 1
	v_cndmask_b32_e64 v35, 0, 1, s[12:13]
	v_readlane_b32 s12, v33, 39
	s_nop 1
	v_cmp_gt_u32_e64 s[12:13], s12, v33
	s_nop 1
	v_addc_co_u32_e64 v34, s[12:13], v34, v35, s[12:13]
	v_readlane_b32 s12, v33, 40
	s_nop 1
	v_cmp_gt_u32_e64 s[12:13], s12, v33
	s_nop 1
	v_cndmask_b32_e64 v35, 0, 1, s[12:13]
	v_readlane_b32 s12, v33, 41
	s_nop 1
	v_cmp_gt_u32_e64 s[12:13], s12, v33
	s_nop 1
	v_addc_co_u32_e64 v34, s[12:13], v34, v35, s[12:13]
	v_readlane_b32 s12, v33, 42
	s_nop 1
	v_cmp_gt_u32_e64 s[12:13], s12, v33
	s_nop 1
	v_cndmask_b32_e64 v35, 0, 1, s[12:13]
	v_readlane_b32 s12, v33, 43
	s_nop 1
	v_cmp_gt_u32_e64 s[12:13], s12, v33
	s_nop 1
	v_addc_co_u32_e64 v34, s[12:13], v34, v35, s[12:13]
	v_readlane_b32 s12, v33, 44
	s_nop 1
	v_cmp_gt_u32_e64 s[12:13], s12, v33
	s_nop 1
	v_cndmask_b32_e64 v35, 0, 1, s[12:13]
	v_readlane_b32 s12, v33, 45
	s_nop 1
	v_cmp_gt_u32_e64 s[12:13], s12, v33
	s_nop 1
	v_addc_co_u32_e64 v34, s[12:13], v34, v35, s[12:13]
	v_readlane_b32 s12, v33, 46
	s_nop 1
	v_cmp_gt_u32_e64 s[12:13], s12, v33
	s_nop 1
	v_cndmask_b32_e64 v35, 0, 1, s[12:13]
	v_readlane_b32 s12, v33, 47
	s_nop 1
	v_cmp_gt_u32_e64 s[12:13], s12, v33
	s_nop 1
	v_addc_co_u32_e64 v34, s[12:13], v34, v35, s[12:13]
	v_readlane_b32 s12, v33, 48
	s_nop 1
	v_cmp_gt_u32_e64 s[12:13], s12, v33
	s_nop 1
	v_cndmask_b32_e64 v35, 0, 1, s[12:13]
	v_readlane_b32 s12, v33, 49
	s_nop 1
	v_cmp_gt_u32_e64 s[12:13], s12, v33
	s_nop 1
	v_addc_co_u32_e64 v33, s[12:13], v34, v35, s[12:13]
	v_cmp_gt_u32_e64 s[12:13], 16, v33
	s_and_b64 s[16:17], vcc, s[12:13]
	s_and_saveexec_b64 s[12:13], s[16:17]
	s_cbranch_execz .LBB0_1189
	v_lshlrev_b32_e32 v30, 7, v30
	v_and_b32_e32 v31, 0x7f, v31
	v_and_b32_e32 v30, 0x3f80, v30
	v_lshl_add_u32 v33, v33, 2, v110
	v_bitop3_b32 v30, v31, s22, v30 bitop3:0x36
	ds_write2st64_b32 v33, v30, v32 offset1:2
